# attention: softmax reference folded into the QK accumulator by one extra bf16 MFMA per accumulator (ones x -m fragment), v_sub before exp removed; rescale path shifts S
# speedup vs baseline: 1.0214x; 1.0067x over previous
; __device__ __forceinline__ void ph_attn(Frame& F) {
;     ...
;         f32x16 o0, o1, pA0, pA1, pB0, pB1;
;         bf16x8_t pk0, pk1, pk2_, pk3;
;         bf16x8_t vf[8], kf[6];
;         { const v4u z = (v4u){0u, 0u, 0u, 0u}; pk0 = __builtin_bit_cast(bf16x8_t, z); pk1 = pk0; pk2_ = pk0; pk3 = pk0;
; #pragma unroll
;           for (int j = 0; j < 8; ++j) vf[j] = pk0; }
; #pragma unroll
;         for (int r = 0; r < 16; ++r) { o0[r] = 0.f; o1[r] = 0.f; pB0[r] = 0.f; pB1[r] = 0.f; }
;         float m_run = -1e30f, l_run = 0.f;
;     ...
;         int kq = AT_KB, kn = 2 * AT_KB, k3 = 3 * AT_KB, kw = 0, vn = 0, v1 = AT_VB, vw = 2 * AT_VB;
.LBB0_998:
	v_mov_b32_e32 v16, v3
	v_mov_b32_e32 v17, v3
	v_mov_b32_e32 v2, v3
	v_mov_b32_e32 v4, v3
	v_mov_b32_e32 v5, v3
	v_mov_b32_e32 v6, v3
	v_mov_b32_e32 v7, v3
	v_mov_b32_e32 v8, v3
	v_mov_b32_e32 v9, v3
	v_mov_b32_e32 v10, v3
	v_mov_b32_e32 v11, v3
	v_mov_b32_e32 v12, v3
	v_mov_b32_e32 v13, v3
	v_mov_b32_e32 v14, v3
	v_mov_b32_e32 v15, v3
	v_mov_b64_e32 v[34:35], v[16:17]
	v_mov_b32_e32 v68, 0
	v_mov_b64_e32 v[32:33], v[14:15]
	v_mov_b64_e32 v[30:31], v[12:13]
	v_mov_b64_e32 v[28:29], v[10:11]
	v_mov_b64_e32 v[26:27], v[8:9]
	v_mov_b64_e32 v[24:25], v[6:7]
	v_mov_b64_e32 v[22:23], v[4:5]
	v_mov_b64_e32 v[20:21], v[2:3]
	v_mov_b64_e32 v[18:19], v[16:17]
	s_add_i32 s37, s36, -1
	s_mov_b32 s38, 0
	s_movk_i32 s40, 0x4800
	s_movk_i32 s39, 0x2400
	s_mov_b32 s41, 0x9c00
	s_movk_i32 s15, 0x6800
	s_movk_i32 s14, 0x3400
	v_mov_b32_e32 v210, 0
	s_mov_b32 s56, 0xf149f2ca
	v_mov_b32_e32 v246, 0x3f80
	v_mov_b32_e32 v247, 0
	v_mov_b32_e32 v248, 0
	v_mov_b32_e32 v249, 0
	v_mov_b32_e32 v250, 0
	v_mov_b32_e32 v251, 0
	v_mov_b32_e32 v252, 0
	v_mov_b32_e32 v253, 0
	v_cndmask_b32_e64 v246, 0, v246, s[2:3]
	v_mov_b32_e32 v209, 0
	v_mov_b64_e32 v[16:17], v[14:15]
	v_mov_b64_e32 v[14:15], v[12:13]
	v_mov_b64_e32 v[12:13], v[10:11]
	v_mov_b64_e32 v[10:11], v[8:9]
	v_mov_b64_e32 v[8:9], v[6:7]
	v_mov_b64_e32 v[6:7], v[4:5]
	v_mov_b64_e32 v[4:5], v[2:3]
	s_mov_b32 s44, 0
	s_mov_b32 s46, 0
	v_mov_b32_e32 v69, v68
	v_mov_b32_e32 v70, v68
	v_mov_b32_e32 v71, v68
	v_mov_b32_e32 v80, v68
	v_mov_b32_e32 v81, v68
	v_mov_b32_e32 v82, v68
	v_mov_b32_e32 v83, v68
	v_mov_b32_e32 v76, v68
	v_mov_b32_e32 v77, v68
	v_mov_b32_e32 v78, v68
	v_mov_b32_e32 v79, v68
	v_mov_b32_e32 v72, v68
	v_mov_b32_e32 v73, v68
	v_mov_b32_e32 v74, v68
	v_mov_b32_e32 v75, v68
	v_mov_b32_e32 v148, v68
	v_mov_b32_e32 v149, v68
	v_mov_b32_e32 v150, v68
	v_mov_b32_e32 v151, v68
	v_mov_b32_e32 v160, v68
	v_mov_b32_e32 v161, v68
	v_mov_b32_e32 v162, v68
	v_mov_b32_e32 v163, v68
	v_mov_b32_e32 v184, v68
	v_mov_b32_e32 v185, v68
	v_mov_b32_e32 v186, v68
	v_mov_b32_e32 v187, v68
	v_mov_b32_e32 v164, v68
	v_mov_b32_e32 v165, v68
	v_mov_b32_e32 v166, v68
	v_mov_b32_e32 v167, v68
	v_mov_b32_e32 v180, v68
	v_mov_b32_e32 v181, v68
	v_mov_b32_e32 v182, v68
	v_mov_b32_e32 v183, v68
	v_mov_b32_e32 v156, v68
	v_mov_b32_e32 v157, v68
	v_mov_b32_e32 v158, v68
	v_mov_b32_e32 v159, v68
	v_mov_b32_e32 v176, v68
	v_mov_b32_e32 v177, v68
	v_mov_b32_e32 v178, v68
	v_mov_b32_e32 v179, v68
	v_mov_b32_e32 v152, v68
	v_mov_b32_e32 v153, v68
	v_mov_b32_e32 v154, v68
	v_mov_b32_e32 v155, v68
.LBB0_999:
	s_add_i32 s42, s46, 4
	s_min_u32 s43, s42, s37
	s_add_i32 s42, s46, 2
	s_min_u32 s45, s42, s37
	s_mulk_i32 s43, 0x3000
	s_add_u32 s48, s10, s43
	s_addc_u32 s49, s11, 0
	s_lshl_b32 s43, s45, 13
	s_add_u32 s50, s12, s43
	s_addc_u32 s51, s13, 0
	s_add_i32 m0, s22, s38
	s_and_b64 s[52:53], s[4:5], exec
	v_lshl_add_u64 v[84:85], s[48:49], 0, v[190:191]
	s_cselect_b32 s49, s49, s51
	s_cselect_b32 s48, s48, s50
	s_cselect_b32 s43, s38, s40
	global_load_lds_dwordx4 v[84:85], off
	v_lshl_add_u64 v[84:85], s[48:49], 0, v[192:193]
	s_add_i32 m0, s21, s43
	s_add_i32 s43, s23, s40
	global_load_lds_dwordx4 v[84:85], off
	v_lshl_add_u64 v[84:85], s[50:51], 0, v[194:195]
	s_add_i32 m0, s43, 0xd000
	s_mov_b32 s43, s39
	global_load_lds_dwordx4 v[84:85], off
	s_mov_b32 s39, s44
	s_mov_b32 s44, s15
	s_mov_b32 s45, s14
	v_mfma_f32_32x32x16_bf16 v[4:19], v[68:71], v[184:187], v[4:19]
	v_max3_f32 v2, v52, v36, v53
	s_nop 0
	v_max3_f32 v2, v2, v37, v54
	s_nop 0
	v_max3_f32 v2, v2, v38, v55
	s_nop 0
	v_max3_f32 v2, v2, v39, v56
	v_mfma_f32_32x32x16_bf16 v[20:35], v[68:71], v[160:163], v[20:35]
	v_max3_f32 v68, v60, v44, v61
	v_max3_f32 v2, v2, v40, v57
	s_nop 0
	v_max3_f32 v68, v68, v45, v62
	v_max3_f32 v2, v2, v41, v58
	s_nop 0
	v_max3_f32 v68, v68, v46, v63
	v_mfma_f32_32x32x16_bf16 v[4:19], v[80:83], v[180:183], v[4:19]
	v_max3_f32 v68, v68, v47, v64
	v_max3_f32 v2, v2, v42, v59
	v_max3_f32 v68, v68, v48, v65
	s_nop 0
	v_max3_f32 v68, v68, v49, v66
	v_mfma_f32_32x32x16_bf16 v[20:35], v[80:83], v[164:167], v[20:35]
	v_max3_f32 v68, v68, v50, v67
	s_nop 0
	v_max3_f32 v2, v2, v43, v68
	s_nop 0
	v_max3_f32 v2, v2, v51, v2
	s_nop 0
	v_mov_b32_e32 v68, v2
	v_mfma_f32_32x32x16_bf16 v[4:19], v[76:79], v[176:179], v[4:19]
	v_mov_b32_e32 v69, v2
	s_nop 1
	v_permlane32_swap_b32_e32 v68, v69
	v_max3_f32 v2, v68, v69, v2
	s_nop 0
	v_cmp_lt_f32_e32 vcc, s56, v2
	v_mfma_f32_32x32x16_bf16 v[20:35], v[76:79], v[156:159], v[20:35]
	v_mfma_f32_32x32x16_bf16 v[20:35], v[72:75], v[152:155], v[20:35]
	v_mfma_f32_32x32x16_bf16 v[4:19], v[72:75], v[148:151], v[4:19]
	s_cbranch_vccz .LBB0_1003
	v_add_f32_e32 v180, v210, v2
	v_cvt_pk_bf16_f32 v180, v180, v180
	v_lshlrev_b32_e32 v180, 16, v180
	v_cndmask_b32_e32 v180, v210, v180, vcc
	v_sub_f32_e32 v2, v210, v180
	v_sub_f32_e32 v84, v180, v210
	v_xor_b32_e32 v250, 0x80000000, v180
	v_min_f32_e32 v2, 0, v2
	v_lshrrev_b32_e32 v250, 16, v250
	v_exp_f32_e32 v2, v2
	v_cndmask_b32_e64 v250, 0, v250, s[2:3]
	s_and_saveexec_b64 s[14:15], s[2:3]
	ds_write_b32 v202, v2
	s_or_b64 exec, exec, s[14:15]
	ds_read_b32 v68, v1
	ds_read_b32 v69, v1 offset:4
	ds_read_b32 v70, v1 offset:8
	ds_read_b32 v71, v1 offset:12
	ds_read_b32 v72, v1 offset:32
	ds_read_b32 v73, v1 offset:36
	ds_read_b32 v74, v1 offset:40
	ds_read_b32 v75, v1 offset:44
	ds_read_b32 v76, v1 offset:64
	ds_read_b32 v77, v1 offset:68
	ds_read_b32 v78, v1 offset:72
	ds_read_b32 v79, v1 offset:76
	ds_read_b32 v80, v1 offset:96
	ds_read_b32 v81, v1 offset:100
	ds_read_b32 v82, v1 offset:104
	ds_read_b32 v83, v1 offset:108
	v_mul_f32_e32 v209, v209, v2
	s_waitcnt lgkmcnt(0)
	v_pk_mul_f32 v[20:21], v[20:21], v[68:69]
	v_pk_mul_f32 v[22:23], v[22:23], v[70:71]
	v_pk_mul_f32 v[24:25], v[24:25], v[72:73]
	v_pk_mul_f32 v[26:27], v[26:27], v[74:75]
	v_pk_mul_f32 v[28:29], v[28:29], v[76:77]
	v_pk_mul_f32 v[30:31], v[30:31], v[78:79]
	v_pk_mul_f32 v[32:33], v[32:33], v[80:81]
	v_pk_mul_f32 v[34:35], v[34:35], v[82:83]
	v_pk_mul_f32 v[4:5], v[4:5], v[68:69]
	v_pk_mul_f32 v[6:7], v[6:7], v[70:71]
	v_pk_mul_f32 v[8:9], v[8:9], v[72:73]
	v_pk_mul_f32 v[10:11], v[10:11], v[74:75]
	v_pk_mul_f32 v[12:13], v[12:13], v[76:77]
	v_pk_mul_f32 v[14:15], v[14:15], v[78:79]
	v_pk_mul_f32 v[16:17], v[16:17], v[80:81]
	v_pk_mul_f32 v[18:19], v[18:19], v[82:83]
	v_sub_f32_e32 v36, v36, v84
	v_sub_f32_e32 v37, v37, v84
	v_sub_f32_e32 v38, v38, v84
	v_sub_f32_e32 v39, v39, v84
	v_sub_f32_e32 v40, v40, v84
	v_sub_f32_e32 v41, v41, v84
	v_sub_f32_e32 v42, v42, v84
	v_sub_f32_e32 v43, v43, v84
	v_sub_f32_e32 v44, v44, v84
	v_sub_f32_e32 v45, v45, v84
	v_sub_f32_e32 v46, v46, v84
	v_sub_f32_e32 v47, v47, v84
	v_sub_f32_e32 v48, v48, v84
	v_sub_f32_e32 v49, v49, v84
	v_sub_f32_e32 v50, v50, v84
	v_sub_f32_e32 v51, v51, v84
	v_sub_f32_e32 v52, v52, v84
	v_sub_f32_e32 v53, v53, v84
	v_sub_f32_e32 v54, v54, v84
	v_sub_f32_e32 v55, v55, v84
	v_sub_f32_e32 v56, v56, v84
	v_sub_f32_e32 v57, v57, v84
	v_sub_f32_e32 v58, v58, v84
	v_sub_f32_e32 v59, v59, v84
	v_sub_f32_e32 v60, v60, v84
	v_sub_f32_e32 v61, v61, v84
	v_sub_f32_e32 v62, v62, v84
	v_sub_f32_e32 v63, v63, v84
	v_sub_f32_e32 v64, v64, v84
	v_sub_f32_e32 v65, v65, v84
	v_sub_f32_e32 v66, v66, v84
	v_sub_f32_e32 v67, v67, v84
	s_mov_b32 s56, 0x41000000
	s_branch .LBB0_1004

.LBB0_1004:
	v_mfma_f32_32x32x16_bf16 v[68:83], v[246:249], v[250:253], 0
	v_mfma_f32_32x32x16_bf16 v[68:83], v[136:139], v[100:103], v[68:83]
	v_add_u32_e32 v2, s45, v189
	ds_read_b128 v[184:187], v2 offset:96
	ds_read_b128 v[210:213], v2 offset:128
	ds_read_b128 v[214:217], v2 offset:6752
	ds_read_b128 v[218:221], v2 offset:160
	ds_read_b128 v[222:225], v2 offset:6784
	ds_read_b128 v[226:229], v2 offset:6816
	v_add_u32_e32 v2, s39, v200
	ds_read_b128 v[176:179], v2 offset:53248
	ds_read_b128 v[164:167], v2 offset:53280
	ds_read_b128 v[230:233], v2 offset:57856
	ds_read_b128 v[238:241], v2 offset:57888
	ds_read_b128 v[160:163], v2 offset:53312
	ds_read_b128 v[156:159], v2 offset:53344
	ds_read_b128 v[242:245], v2 offset:57920
	ds_read_b128 v[152:155], v2 offset:57952
	v_mfma_f32_32x32x16_bf16 v[84:99], v[246:249], v[250:253], 0
	v_mfma_f32_32x32x16_bf16 v[84:99], v[132:135], v[100:103], v[84:99]
	v_exp_f32_e32 v52, v52
	v_exp_f32_e32 v183, v36
	v_exp_f32_e32 v132, v53
	v_exp_f32_e32 v53, v54
	v_mfma_f32_32x32x16_bf16 v[68:83], v[144:147], v[104:107], v[68:83]
	v_mov_b32_e32 v2, v38
	v_mov_b32_e32 v36, v55
	v_exp_f32_e32 v55, v56
	v_exp_f32_e32 v56, v40
	v_mfma_f32_32x32x16_bf16 v[84:99], v[128:131], v[104:107], v[84:99]
	v_exp_f32_e32 v40, v39
	v_mov_b32_e32 v38, v57
	v_mov_b32_e32 v57, v58
	v_exp_f32_e32 v58, v41
	v_mfma_f32_32x32x16_bf16 v[68:83], v[140:143], v[108:111], v[68:83]
	v_add_u32_e32 v181, s44, v189
	ds_read_b128 v[144:147], v181
	ds_read_b128 v[172:175], v181 offset:32
	ds_read_b128 v[136:139], v181 offset:6656
	ds_read_b128 v[168:171], v181 offset:64
	ds_read_b128 v[148:151], v181 offset:6688
	ds_read_b128 v[140:143], v181 offset:6720
	v_exp_f32_e32 v54, v2
	v_exp_f32_e32 v2, v37
	v_mfma_f32_32x32x16_bf16 v[84:99], v[124:127], v[108:111], v[84:99]
	v_exp_f32_e32 v124, v59
	v_exp_f32_e32 v36, v36
	v_exp_f32_e32 v57, v57
	v_exp_f32_e32 v41, v60
	v_add_f32_e32 v133, v52, v183
	v_add_f32_e32 v37, v53, v54
	s_waitcnt lgkmcnt(14)
	v_mfma_f32_32x32x16_bf16 v[68:83], v[214:217], v[112:115], v[68:83]
	v_exp_f32_e32 v214, v42
	v_exp_f32_e32 v59, v44
	v_exp_f32_e32 v60, v43
	v_exp_f32_e32 v126, v61
	v_mfma_f32_32x32x16_bf16 v[84:99], v[184:187], v[112:115], v[84:99]
	v_mov_b32_e32 v43, v62
	v_exp_f32_e32 v62, v45
	v_exp_f32_e32 v128, v63
	v_exp_f32_e32 v63, v64
	v_mfma_f32_32x32x16_bf16 v[68:83], v[222:225], v[116:119], v[68:83]
	v_exp_f32_e32 v216, v48
	v_exp_f32_e32 v64, v47
	v_exp_f32_e32 v130, v65
	v_mfma_f32_32x32x16_bf16 v[84:99], v[210:213], v[116:119], v[84:99]
	v_exp_f32_e32 v61, v43
	v_exp_f32_e32 v65, v66
	v_exp_f32_e32 v215, v46
	v_exp_f32_e32 v185, v50
	v_mfma_f32_32x32x16_bf16 v[68:83], v[226:229], v[120:123], v[68:83]
	v_exp_f32_e32 v66, v49
	v_exp_f32_e32 v134, v67
	v_add_f32_e32 v39, v55, v56
	v_exp_f32_e32 v38, v38
	v_add_f32_e32 v125, v57, v214
	v_mfma_f32_32x32x16_bf16 v[84:99], v[218:221], v[120:123], v[84:99]
	v_add_f32_e32 v127, v41, v59
	v_add_f32_e32 v129, v61, v215
	v_add_f32_e32 v131, v63, v216
	v_add_f32_e32 v135, v65, v185
	v_exp_f32_e32 v184, v51
	v_cvt_pk_bf16_f32 v42, v52, v132
	v_cvt_pk_bf16_f32 v43, v53, v36
	v_cvt_pk_bf16_f32 v44, v55, v38
	v_cvt_pk_bf16_f32 v45, v57, v124
	v_cvt_pk_bf16_f32 v46, v41, v126
	v_cvt_pk_bf16_f32 v47, v61, v128
	v_cvt_pk_bf16_f32 v48, v63, v130
	v_cvt_pk_bf16_f32 v49, v65, v134
	v_cvt_pk_bf16_f32 v50, v183, v2
	v_cvt_pk_bf16_f32 v51, v54, v40
	v_cvt_pk_bf16_f32 v52, v56, v58
	v_cvt_pk_bf16_f32 v53, v214, v60
	v_cvt_pk_bf16_f32 v54, v59, v62
	v_cvt_pk_bf16_f32 v55, v215, v64
	v_cvt_pk_bf16_f32 v56, v216, v66
	v_cvt_pk_bf16_f32 v57, v185, v184
	s_add_i32 s14, s46, 5
	s_min_u32 s14, s14, s37
	s_add_i32 s15, s46, 3
	s_min_u32 s46, s15, s37
	s_mulk_i32 s14, 0x3000
	s_add_u32 s14, s10, s14
	s_addc_u32 s15, s11, 0
	s_lshl_b32 s46, s46, 13
	s_add_u32 s46, s12, s46
	s_addc_u32 s47, s13, 0
	s_add_i32 m0, s22, s45
	s_and_b64 s[48:49], s[4:5], exec
	s_waitcnt vmcnt(3) lgkmcnt(0)
	s_barrier
	v_lshl_add_u64 v[186:187], s[14:15], 0, v[190:191]
	s_cselect_b32 s15, s15, s47
	s_cselect_b32 s14, s14, s46
	global_load_lds_dwordx4 v[186:187], off
	v_lshl_add_u64 v[186:187], s[14:15], 0, v[192:193]
	s_cselect_b32 s14, s45, s39
	s_add_i32 m0, s21, s14
	s_add_i32 s14, s23, s39
	global_load_lds_dwordx4 v[186:187], off
	v_lshl_add_u64 v[186:187], s[46:47], 0, v[194:195]
	s_add_i32 m0, s14, 0xd000
	s_nop 0
	global_load_lds_dwordx4 v[186:187], off
	v_mfma_f32_32x32x16_bf16 v[4:19], v[42:45], v[230:233], v[4:19]
	v_max3_f32 v41, v84, v68, v85
	v_max3_f32 v59, v92, v76, v93
	v_add_f32_e32 v132, v132, v2
	v_max3_f32 v41, v41, v69, v86
	v_max3_f32 v59, v59, v77, v94
	s_nop 0
	v_max3_f32 v41, v41, v70, v87
	v_mfma_f32_32x32x16_bf16 v[20:35], v[42:45], v[176:179], v[20:35]
	v_max3_f32 v41, v41, v71, v88
	v_max3_f32 v59, v59, v78, v95
	v_max3_f32 v41, v41, v72, v89
	v_max3_f32 v59, v59, v79, v96
	s_nop 0
	v_max3_f32 v41, v41, v73, v90
	v_mfma_f32_32x32x16_bf16 v[4:19], v[46:49], v[238:241], v[4:19]
	v_max3_f32 v183, v41, v74, v91
	v_add_f32_e32 v41, v132, v133
	v_max3_f32 v59, v59, v80, v97
	v_add_f32_e64 v36, v36, v40
	v_add_f32_e64 v37, v37, v41
	v_max3_f32 v59, v59, v81, v98
	v_mfma_f32_32x32x16_bf16 v[20:35], v[46:49], v[164:167], v[20:35]
	v_max3_f32 v186, v59, v82, v99
	v_add_f32_e32 v59, v36, v37
	v_add_f32_e32 v36, v38, v58
	v_add_f32_e32 v37, v39, v59
	v_add_f32_e32 v61, v36, v37
	v_add_f32_e32 v36, v124, v60
	v_add_f32_e32 v37, v125, v61
	v_mfma_f32_32x32x16_bf16 v[4:19], v[50:53], v[242:245], v[4:19]
	v_add_f32_e32 v63, v36, v37
	v_add_f32_e32 v36, v126, v62
	v_add_f32_e32 v37, v127, v63
	v_add_f32_e32 v65, v36, v37
	v_add_f32_e32 v36, v128, v64
	v_add_f32_e32 v37, v129, v65
	v_mfma_f32_32x32x16_bf16 v[20:35], v[50:53], v[160:163], v[20:35]
	v_add_f32_e32 v67, v36, v37
	v_add_f32_e32 v36, v130, v66
	v_add_f32_e32 v37, v131, v67
	v_add_f32_e32 v185, v36, v37
	v_add_f32_e32 v36, v134, v184
	v_add_f32_e32 v37, v135, v185
	v_mfma_f32_32x32x16_bf16 v[20:35], v[54:57], v[156:159], v[20:35]
	v_add_f32_e32 v2, v36, v37
	v_max3_f32 v36, v183, v75, v186
	v_add_f32_e32 v2, v209, v2
	v_max3_f32 v36, v36, v83, v36
	s_nop 0
	v_mov_b32_e32 v37, v36
	v_mov_b32_e32 v38, v36
	v_mfma_f32_32x32x16_bf16 v[4:19], v[54:57], v[152:155], v[4:19]
	s_nop 0
	v_permlane32_swap_b32_e32 v37, v38
	v_max3_f32 v36, v37, v38, v36
	s_nop 0
	v_cmp_lt_f32_e32 vcc, s56, v36
	s_cbranch_vccz .LBB0_1008
	s_nop 0
	v_add_f32_e32 v210, v180, v36
	v_cvt_pk_bf16_f32 v210, v210, v210
	v_lshlrev_b32_e32 v210, 16, v210
	v_cndmask_b32_e32 v210, v180, v210, vcc
	v_sub_f32_e32 v36, v180, v210
	v_sub_f32_e32 v186, v210, v180
	v_xor_b32_e32 v250, 0x80000000, v210
	v_min_f32_e32 v36, 0, v36
	v_lshrrev_b32_e32 v250, 16, v250
	v_exp_f32_e32 v36, v36
	v_cndmask_b32_e64 v250, 0, v250, s[2:3]
	s_and_saveexec_b64 s[14:15], s[2:3]
	ds_write_b32 v202, v36
	s_or_b64 exec, exec, s[14:15]
	v_mul_f32_e32 v2, v2, v36
	ds_read_b32 v36, v1
	ds_read_b32 v37, v1 offset:4
	ds_read_b32 v38, v1 offset:8
	ds_read_b32 v39, v1 offset:12
	ds_read_b32 v40, v1 offset:32
	ds_read_b32 v41, v1 offset:36
	ds_read_b32 v42, v1 offset:40
	ds_read_b32 v43, v1 offset:44
	ds_read_b32 v44, v1 offset:64
	ds_read_b32 v45, v1 offset:68
	ds_read_b32 v46, v1 offset:72
	ds_read_b32 v47, v1 offset:76
	ds_read_b32 v48, v1 offset:96
	ds_read_b32 v49, v1 offset:100
	ds_read_b32 v50, v1 offset:104
	ds_read_b32 v51, v1 offset:108
	s_waitcnt lgkmcnt(0)
	v_pk_mul_f32 v[20:21], v[20:21], v[36:37]
	v_pk_mul_f32 v[22:23], v[22:23], v[38:39]
	v_pk_mul_f32 v[24:25], v[24:25], v[40:41]
	v_pk_mul_f32 v[26:27], v[26:27], v[42:43]
	v_pk_mul_f32 v[28:29], v[28:29], v[44:45]
	v_pk_mul_f32 v[30:31], v[30:31], v[46:47]
	v_pk_mul_f32 v[32:33], v[32:33], v[48:49]
	v_pk_mul_f32 v[34:35], v[34:35], v[50:51]
	v_pk_mul_f32 v[4:5], v[4:5], v[36:37]
	v_pk_mul_f32 v[6:7], v[6:7], v[38:39]
	v_pk_mul_f32 v[8:9], v[8:9], v[40:41]
	v_pk_mul_f32 v[10:11], v[10:11], v[42:43]
	v_pk_mul_f32 v[12:13], v[12:13], v[44:45]
	v_pk_mul_f32 v[14:15], v[14:15], v[46:47]
	v_pk_mul_f32 v[16:17], v[16:17], v[48:49]
	v_pk_mul_f32 v[18:19], v[18:19], v[50:51]
	v_sub_f32_e32 v68, v68, v186
	v_sub_f32_e32 v69, v69, v186
	v_sub_f32_e32 v70, v70, v186
	v_sub_f32_e32 v71, v71, v186
	v_sub_f32_e32 v72, v72, v186
	v_sub_f32_e32 v73, v73, v186
	v_sub_f32_e32 v74, v74, v186
	v_sub_f32_e32 v75, v75, v186
	v_sub_f32_e32 v76, v76, v186
	v_sub_f32_e32 v77, v77, v186
	v_sub_f32_e32 v78, v78, v186
	v_sub_f32_e32 v79, v79, v186
	v_sub_f32_e32 v80, v80, v186
	v_sub_f32_e32 v81, v81, v186
	v_sub_f32_e32 v82, v82, v186
	v_sub_f32_e32 v83, v83, v186
	v_sub_f32_e32 v84, v84, v186
	v_sub_f32_e32 v85, v85, v186
	v_sub_f32_e32 v86, v86, v186
	v_sub_f32_e32 v87, v87, v186
	v_sub_f32_e32 v88, v88, v186
	v_sub_f32_e32 v89, v89, v186
	v_sub_f32_e32 v90, v90, v186
	v_sub_f32_e32 v91, v91, v186
	v_sub_f32_e32 v92, v92, v186
	v_sub_f32_e32 v93, v93, v186
	v_sub_f32_e32 v94, v94, v186
	v_sub_f32_e32 v95, v95, v186
	v_sub_f32_e32 v96, v96, v186
	v_sub_f32_e32 v97, v97, v186
	v_sub_f32_e32 v98, v98, v186
	v_sub_f32_e32 v99, v99, v186
	s_mov_b32 s56, 0x41000000
	s_branch .LBB0_1009

.LBB0_1009:
	v_mfma_f32_32x32x16_bf16 v[36:51], v[246:249], v[250:253], 0
	v_mfma_f32_32x32x16_bf16 v[36:51], v[136:139], v[100:103], v[36:51]
	v_add_u32_e32 v52, s43, v200
	ds_read_b128 v[212:215], v181 offset:96
	ds_read_b128 v[216:219], v181 offset:128
	ds_read_b128 v[220:223], v181 offset:6752
	ds_read_b128 v[224:227], v181 offset:160
	ds_read_b128 v[228:231], v181 offset:6784
	ds_read_b128 v[238:241], v181 offset:6816
	ds_read_b128 v[160:163], v52 offset:53248
	ds_read_b128 v[164:167], v52 offset:53280
	ds_read_b128 v[184:187], v52 offset:57856
	ds_read_b128 v[180:183], v52 offset:57888
	ds_read_b128 v[156:159], v52 offset:53312
	ds_read_b128 v[152:155], v52 offset:53344
	v_add_u32_e32 v209, s41, v189
	v_mfma_f32_32x32x16_bf16 v[36:51], v[148:151], v[104:107], v[36:51]
	ds_read_b128 v[176:179], v52 offset:57920
	ds_read_b128 v[148:151], v52 offset:57952
	v_exp_f32_e32 v211, v84
	v_exp_f32_e32 v232, v68
	v_exp_f32_e32 v233, v85
	v_mfma_f32_32x32x16_bf16 v[52:67], v[246:249], v[250:253], 0
	v_mfma_f32_32x32x16_bf16 v[52:67], v[144:147], v[100:103], v[52:67]
	v_exp_f32_e32 v235, v69
	v_add_f32_e32 v68, v211, v232
	v_add_f32_e32 v68, 0, v68
	v_add_f32_e32 v69, v233, v235
	v_add_f32_e32 v68, v69, v68
	v_mfma_f32_32x32x16_bf16 v[52:67], v[172:175], v[104:107], v[52:67]
	v_exp_f32_e32 v173, v70
	v_exp_f32_e32 v172, v86
	v_exp_f32_e32 v174, v87
	v_exp_f32_e32 v175, v71
	v_add_f32_e32 v69, v172, v173
	v_add_f32_e32 v68, v69, v68
	v_mfma_f32_32x32x16_bf16 v[52:67], v[168:171], v[108:111], v[52:67]
	v_add_f32_e32 v69, v174, v175
	v_add_f32_e32 v168, v69, v68
	v_exp_f32_e32 v71, v88
	v_exp_f32_e32 v85, v72
	v_exp_f32_e32 v70, v89
	v_exp_f32_e32 v84, v73
	v_exp_f32_e32 v73, v90
	v_exp_f32_e32 v87, v74
	v_exp_f32_e32 v72, v91
	v_exp_f32_e32 v86, v75
	v_pk_add_f32 v[68:69], v[70:71], v[84:85]
	v_mfma_f32_32x32x16_bf16 v[36:51], v[140:143], v[108:111], v[36:51]
	v_add_f32_e32 v69, v69, v168
	v_add_f32_e32 v74, v68, v69
	v_add_f32_e64 v68, v72, v86
	v_add_f32_e64 v69, v73, v87
	ds_read_b128 v[132:135], v209
	ds_read_b128 v[128:131], v209 offset:32
	ds_read_b128 v[136:139], v209 offset:6656
	ds_read_b128 v[124:127], v209 offset:64
	v_add_f32_e32 v69, v69, v74
	v_add_f32_e32 v168, v68, v69
	v_exp_f32_e32 v75, v92
	v_exp_f32_e32 v89, v76
	v_exp_f32_e32 v74, v93
	v_exp_f32_e32 v88, v77
	v_exp_f32_e32 v77, v94
	s_waitcnt lgkmcnt(12)
	v_mfma_f32_32x32x16_bf16 v[36:51], v[220:223], v[112:115], v[36:51]
	v_exp_f32_e32 v91, v78
	v_exp_f32_e32 v76, v95
	v_exp_f32_e32 v90, v79
	v_pk_add_f32 v[68:69], v[74:75], v[88:89]
	ds_read_b128 v[144:147], v209 offset:6688
	ds_read_b128 v[140:143], v209 offset:6720
	v_mfma_f32_32x32x16_bf16 v[52:67], v[212:215], v[112:115], v[52:67]
	v_add_f32_e32 v69, v69, v168
	v_add_f32_e32 v78, v68, v69
	v_add_f32_e64 v68, v76, v90
	v_add_f32_e64 v69, v77, v91
	v_add_f32_e32 v69, v69, v78
	v_add_f32_e32 v168, v68, v69
	v_mfma_f32_32x32x16_bf16 v[36:51], v[228:231], v[116:119], v[36:51]
	v_exp_f32_e32 v79, v96
	v_exp_f32_e32 v93, v80
	v_exp_f32_e32 v78, v97
	v_exp_f32_e32 v92, v81
	v_mfma_f32_32x32x16_bf16 v[52:67], v[216:219], v[116:119], v[52:67]
	v_exp_f32_e32 v95, v98
	v_exp_f32_e32 v97, v82
	v_exp_f32_e32 v94, v99
	v_mfma_f32_32x32x16_bf16 v[36:51], v[238:241], v[120:123], v[36:51]
	v_exp_f32_e32 v96, v83
	v_pk_add_f32 v[68:69], v[78:79], v[92:93]
	s_nop 0
	v_add_f32_e32 v69, v69, v168
	v_add_f32_e32 v80, v68, v69
	v_pk_add_f32 v[68:69], v[94:95], v[96:97]
	v_mfma_f32_32x32x16_bf16 v[52:67], v[224:227], v[120:123], v[52:67]
	v_add_f32_e32 v69, v69, v80
	v_add_f32_e32 v68, v68, v69
	v_add_f32_e32 v209, v2, v68
	v_cvt_pk_bf16_f32 v68, v211, v233
	v_cvt_pk_bf16_f32 v69, v172, v174
	v_cvt_pk_bf16_f32 v70, v71, v70
	v_cvt_pk_bf16_f32 v71, v73, v72
	v_cvt_pk_bf16_f32 v80, v75, v74
	v_cvt_pk_bf16_f32 v81, v77, v76
	v_cvt_pk_bf16_f32 v82, v79, v78
	v_cvt_pk_bf16_f32 v83, v95, v94
	v_cvt_pk_bf16_f32 v76, v232, v235
	v_cvt_pk_bf16_f32 v77, v173, v175
	v_cvt_pk_bf16_f32 v78, v85, v84
	v_cvt_pk_bf16_f32 v79, v87, v86
	v_cvt_pk_bf16_f32 v72, v89, v88
	v_cvt_pk_bf16_f32 v73, v91, v90
	v_cvt_pk_bf16_f32 v74, v93, v92
	v_cvt_pk_bf16_f32 v75, v97, v96
	s_waitcnt vmcnt(3) lgkmcnt(0)
	s_barrier
	s_cmp_ge_u32 s42, s36
	s_cbranch_scc1 .LBB0_1011
	s_mov_b32 s14, s41
	s_mov_b32 s15, s38
	s_mov_b32 s41, s45
	s_mov_b32 s38, s44
	s_mov_b32 s44, s40
	s_mov_b32 s40, s43
	s_mov_b32 s46, s42
	s_branch .LBB0_999
